# GEMM tile prologue de-serialised: all 14 LDS-DMA stage loads issued before the first counted wait (vmcnt 10 then 6)
# speedup vs baseline: 1.0091x; 1.0091x over previous
; #define STAGE(bufoff,gbase,voff) do{ _Pragma("unroll") for(int _i=0;_i<2;++_i) \
;     __builtin_amdgcn_global_load_lds((const unsigned*)((const char*)(gbase)+(voff)[_i]),(LAS unsigned*)(lds+(bufoff)+ldsw+_i*8192),16,0,0);}while(0)
; #define WAIT_V(n) asm volatile("s_waitcnt vmcnt(" #n ")":::"memory")
; #define BAR __builtin_amdgcn_s_barrier()
; DEVI void gemm_tile(const GJob& jb, int brow, int bcol, unsigned char* shm_) {
;     ...
;   f32x4 acc[2][2][4][2];
; #pragma unroll
;   for (int a = 0; a < 2; ++a)
; #pragma unroll
;     for (int b = 0; b < 2; ++b)
; #pragma unroll
;       for (int m = 0; m < 4; ++m)
; #pragma unroll
;         for (int n = 0; n < 2; ++n) acc[a][b][m][n] = (f32x4){0.f, 0.f, 0.f, 0.f};
;   bf16x8 At[4][2], B0[2][2], B1[2][2];
;   const int nt = K / BK;
;   const char* cA = (const char*)jb.A + (size_t)brow * lda * 2; const char* cB = (const char*)jb.Bt + (size_t)bcol * ldb * 2;
;   STAGE(SB(0,0),cB,voffB); STAGE(SA(0,0),cA,voffA);
;   STAGE(SB(0,1),cB+hB,voffB); STAGE(SA(0,1),cA+hA,voffA);
;   if (wr == 1) BAR;
;   WAIT_V(4); BAR;
;   STAGE(SB(1,0),cB+128,voffB); STAGE(SA(1,0),cA+128,voffA); STAGE(SB(1,1),cB+hB+128,voffB);
;   WAIT_V(6); BAR;
.LBB0_412:
	v_mov_b32_e32 v3, v1
	v_lshl_add_u64 v[6:7], s[8:9], 0, v[2:3]
	v_mov_b32_e32 v5, v1
	v_lshl_add_u64 v[8:9], s[8:9], 0, v[4:5]
	s_add_i32 m0, s69, 0x18000
	v_lshl_add_u64 v[6:7], v[6:7], 0, s[72:73]
	v_lshl_add_u64 v[10:11], s[10:11], 0, v[0:1]
	v_mov_b32_e32 v139, v1
	s_lshl_b32 s8, s57, 5
	global_load_lds_dwordx4 v[6:7], off
	v_lshl_add_u64 v[6:7], v[8:9], 0, s[72:73]
	s_add_i32 m0, s69, 0x1a000
	s_add_i32 s57, s69, 0x8000
	v_lshl_add_u64 v[12:13], s[10:11], 0, v[138:139]
	s_lshl_b32 s47, s52, 6
	s_lshl_b32 s9, s52, 13
	global_load_lds_dwordx4 v[6:7], off
	v_lshl_add_u64 v[6:7], v[10:11], 0, s[72:73]
	s_mov_b32 m0, s57
	s_add_i32 s52, s69, 0xa000
	v_lshl_add_u64 v[2:3], s[82:83], 0, v[2:3]
	global_load_lds_dwordx4 v[6:7], off
	v_lshl_add_u64 v[6:7], v[12:13], 0, s[72:73]
	s_mov_b32 m0, s52
	v_lshl_add_u64 v[4:5], s[82:83], 0, v[4:5]
	global_load_lds_dwordx4 v[6:7], off
	s_add_i32 m0, s69, 0x1c000
	v_lshl_add_u64 v[2:3], v[2:3], 0, s[72:73]
	global_load_lds_dwordx4 v[2:3], off
	v_lshl_add_u64 v[2:3], v[4:5], 0, s[72:73]
	s_add_i32 m0, s69, 0x1e000
	v_and_b32_e32 v159, 15, v137
	global_load_lds_dwordx4 v[2:3], off
	v_lshlrev_b32_e32 v14, 1, v158
	v_lshlrev_b32_e32 v15, 2, v137
	s_and_b32 s68, s8, 0x60
	s_waitcnt vmcnt(10)
	s_barrier
	s_waitcnt vmcnt(6)
	v_lshl_or_b32 v14, v159, 6, v14
	v_and_b32_e32 v15, 32, v15
	s_lshl_b32 s8, s68, 7
	v_mov_b32_e32 v125, 0
	v_bitop3_b32 v161, v14, s8, v15 bitop3:0xde
	v_bitop3_b32 v160, v14, s9, v15 bitop3:0xde
	s_andn2_b64 vcc, exec, s[78:79]
	v_mov_b32_e32 v124, v125
	v_mov_b32_e32 v123, v125
	v_mov_b32_e32 v122, v125
	v_mov_b32_e32 v129, v125
	v_mov_b32_e32 v128, v125
	v_mov_b32_e32 v127, v125
	v_mov_b32_e32 v126, v125
	v_mov_b32_e32 v121, v125
	v_mov_b32_e32 v120, v125
	v_mov_b32_e32 v119, v125
	v_mov_b32_e32 v118, v125
	v_mov_b32_e32 v117, v125
	v_mov_b32_e32 v116, v125
	v_mov_b32_e32 v115, v125
	v_mov_b32_e32 v114, v125
	v_mov_b32_e32 v113, v125
	v_mov_b32_e32 v112, v125
	v_mov_b32_e32 v111, v125
	v_mov_b32_e32 v110, v125
	v_mov_b32_e32 v109, v125
	v_mov_b32_e32 v108, v125
	v_mov_b32_e32 v107, v125
	v_mov_b32_e32 v106, v125
	v_mov_b32_e32 v105, v125
	v_mov_b32_e32 v104, v125
	v_mov_b32_e32 v103, v125
	v_mov_b32_e32 v102, v125
	v_mov_b32_e32 v101, v125
	v_mov_b32_e32 v100, v125
	v_mov_b32_e32 v99, v125
	v_mov_b32_e32 v98, v125
	v_mov_b32_e32 v97, v125
	v_mov_b32_e32 v96, v125
	v_mov_b32_e32 v95, v125
	v_mov_b32_e32 v94, v125
	v_mov_b32_e32 v93, v125
	v_mov_b32_e32 v92, v125
	v_mov_b32_e32 v91, v125
	v_mov_b32_e32 v90, v125
	v_mov_b32_e32 v89, v125
	v_mov_b32_e32 v88, v125
	v_mov_b32_e32 v87, v125
	v_mov_b32_e32 v86, v125
	v_mov_b32_e32 v85, v125
	v_mov_b32_e32 v84, v125
	v_mov_b32_e32 v83, v125
	v_mov_b32_e32 v82, v125
	v_mov_b32_e32 v81, v125
	v_mov_b32_e32 v80, v125
	v_mov_b32_e32 v79, v125
	v_mov_b32_e32 v78, v125
	v_mov_b32_e32 v77, v125
	v_mov_b32_e32 v76, v125
	v_mov_b32_e32 v75, v125
	v_mov_b32_e32 v74, v125
	v_mov_b32_e32 v73, v125
	v_mov_b32_e32 v72, v125
	v_mov_b32_e32 v71, v125
	v_mov_b32_e32 v70, v125
	v_mov_b32_e32 v69, v125
	v_mov_b32_e32 v68, v125
	v_mov_b32_e32 v67, v125
	v_mov_b32_e32 v66, v125
	v_mov_b32_e32 v65, v125
	v_mov_b32_e32 v64, v125
	v_mov_b32_e32 v63, v125
	v_mov_b32_e32 v62, v125
	v_mov_b32_e32 v61, v125
	v_mov_b32_e32 v60, v125
	v_mov_b32_e32 v59, v125
	v_mov_b32_e32 v58, v125
	v_mov_b32_e32 v57, v125
	v_mov_b32_e32 v56, v125
	v_mov_b32_e32 v55, v125
	v_mov_b32_e32 v54, v125
	v_mov_b32_e32 v53, v125
	v_mov_b32_e32 v52, v125
	v_mov_b32_e32 v51, v125
	v_mov_b32_e32 v50, v125
	v_mov_b32_e32 v49, v125
	v_mov_b32_e32 v48, v125
	v_mov_b32_e32 v47, v125
	v_mov_b32_e32 v46, v125
	v_mov_b32_e32 v45, v125
	v_mov_b32_e32 v44, v125
	v_mov_b32_e32 v43, v125
	v_mov_b32_e32 v42, v125
	v_mov_b32_e32 v41, v125
	v_mov_b32_e32 v40, v125
	v_mov_b32_e32 v39, v125
	v_mov_b32_e32 v38, v125
	v_mov_b32_e32 v37, v125
	v_mov_b32_e32 v36, v125
	v_mov_b32_e32 v35, v125
	v_mov_b32_e32 v34, v125
	v_mov_b32_e32 v33, v125
	v_mov_b32_e32 v32, v125
	v_mov_b32_e32 v31, v125
	v_mov_b32_e32 v30, v125
	v_mov_b32_e32 v29, v125
	v_mov_b32_e32 v28, v125
	v_mov_b32_e32 v27, v125
	v_mov_b32_e32 v26, v125
	v_mov_b32_e32 v25, v125
	v_mov_b32_e32 v24, v125
	v_mov_b32_e32 v23, v125
	v_mov_b32_e32 v22, v125
	v_mov_b32_e32 v21, v125
	v_mov_b32_e32 v20, v125
	v_mov_b32_e32 v19, v125
	v_mov_b32_e32 v18, v125
	v_mov_b32_e32 v17, v125
	v_mov_b32_e32 v16, v125
	v_mov_b32_e32 v15, v125
	v_mov_b32_e32 v14, v125
	v_mov_b32_e32 v13, v125
	v_mov_b32_e32 v12, v125
	v_mov_b32_e32 v11, v125
	v_mov_b32_e32 v10, v125
	v_mov_b32_e32 v9, v125
	v_mov_b32_e32 v8, v125
	v_mov_b32_e32 v7, v125
	v_mov_b32_e32 v6, v125
	v_mov_b32_e32 v5, v125
	v_mov_b32_e32 v4, v125
	v_mov_b32_e32 v3, v125
	v_mov_b32_e32 v2, v125
	s_barrier
	s_cbranch_vccnz .LBB0_422
; DEVI f32x4 ld_bf4(const bf16_t* p) { u32x2 u = *(const u32x2*)p; return (f32x4){bf_lo(u.x), bf_hi(u.x), bf_lo(u.y), bf_hi(u.y)}; }
; DEVI void gemm_tile(const GJob& jb, int brow, int bcol, unsigned char* shm_) {
;     ...
;   f32x4 acc[2][2][4][2];
; #pragma unroll
;   for (int a = 0; a < 2; ++a)
; #pragma unroll
;     for (int b = 0; b < 2; ++b)
; #pragma unroll
;       for (int m = 0; m < 4; ++m)
; #pragma unroll
;         for (int n = 0; n < 2; ++n) acc[a][b][m][n] = (f32x4){0.f, 0.f, 0.f, 0.f};
;     ...
;     if (jb.mode == 7 && (t == 16 || t == 32)) {
;       const int seg = (t >> 4) - 1;
;       const bf16_t* gp = (const bf16_t*)jb.aux + (size_t)(brow + wr * 64 + fr) * NGATE + seg * 2048 + bcol + wc * 32 + fq * 8;
; #pragma unroll
;       for (int ai = 0; ai < 2; ++ai)
; #pragma unroll
;         for (int m = 0; m < 4; ++m)
; #pragma unroll
;           for (int bj = 0; bj < 2; ++bj)
; #pragma unroll
;             for (int n = 0; n < 2; ++n) {
;               const bf16_t* g = gp + (size_t)(ai * HALF + m * 16) * NGATE + bj * HALF + n * 4;
;               const f32x4 g0 = ld_bf4(g), g1 = ld_bf4(g + 2048);
; #pragma unroll
;               for (int e = 0; e < 4; ++e) acc[ai][bj][m][n][e] *= g0[e] * __builtin_amdgcn_rcpf(fmaxf(g1[e], 1e-30f));
;             }
;     }
;     const char* a1 = cA + (size_t)(t + 1) * 128; const char* a2 = a1 + 128; const char* a3 = a2 + 128;
;     const char* b2 = cB + (size_t)(t + 2) * 128; const char* b3 = b2 + 128;
	s_lshl_b32 s1, s1, 3
	s_add_i32 s1, s20, s1
	s_sub_i32 s1, s1, s5
	s_sub_i32 s1, s1, s58
	s_lshl_b32 s0, s0, 3
	s_sub_i32 s5, s1, s0
	s_lshl_b32 s58, s5, 8
	s_add_i32 s0, s58, s47
	v_add_u32_e32 v2, s0, v159
	v_mad_i64_i32 v[2:3], s[0:1], v2, s33, 0
	s_and_b32 s0, s46, 0xc0
	v_and_b32_e32 v7, 48, v137
	v_or3_b32 v2, v2, s0, v7
	s_lshl_b64 s[0:1], s[12:13], 1
	s_add_u32 s8, s49, s0
	s_addc_u32 s9, s42, s1
	s_lshl_b32 s5, s5, 9
	s_ashr_i32 s13, s58, 31
	s_bitset1_b32 s5, 8
	v_bfe_u32 v6, v140, 6, 4
	v_and_b32_e32 v4, -16, v141
	v_lshl_add_u64 v[140:141], s[8:9], 0, v[2:3]
	s_mul_i32 s8, s96, s13
	s_mul_hi_u32 s9, s96, s5
	s_add_i32 s8, s9, s8
	s_mul_i32 s9, s97, s5
	v_add_u32_e32 v2, v4, v6
	v_and_b32_e32 v5, -16, v142
	s_add_i32 s44, s8, s9
	s_mul_i32 s5, s96, s5
	v_mad_u64_u32 v[2:3], s[8:9], s96, v2, v[130:131]
	s_add_u32 s8, s40, s5
	v_add_u32_e32 v4, v5, v6
	s_addc_u32 s9, s41, s44
	v_mad_u64_u32 v[4:5], s[44:45], s96, v4, v[130:131]
	v_add_lshl_u32 v2, v2, v131, 1
	v_mov_b32_e32 v3, v1
	v_add_lshl_u32 v4, v4, v131, 1
	v_mov_b32_e32 v5, v1
	v_lshl_add_u64 v[142:143], s[8:9], 0, v[2:3]
	v_lshl_add_u64 v[144:145], s[8:9], 0, v[4:5]
	s_mul_i32 s5, s66, s13
	s_mul_hi_u32 s8, s66, s58
	s_add_i32 s5, s8, s5
	s_mul_i32 s8, s67, s58
	s_add_i32 s5, s5, s8
	s_mul_i32 s8, s66, s58
	s_add_u32 s8, s40, s8
	s_addc_u32 s9, s41, s5
	v_lshl_add_u64 v[146:147], s[8:9], 0, v[2:3]
	s_add_u32 s0, s0, 0x100
	v_lshlrev_b32_e32 v2, 1, v6
	s_addc_u32 s1, s1, 0
	v_and_b32_e32 v6, 24, v2
	s_mul_i32 s1, s18, s1
	s_mul_hi_u32 s5, s18, s0
	v_add_u32_e32 v2, v135, v6
	s_add_i32 s1, s5, s1
	s_mul_i32 s5, s19, s0
	v_add3_u32 v2, v2, v136, v132
	v_add_u32_e32 v6, v133, v6
	s_add_i32 s5, s1, s5
	s_mul_i32 s13, s18, s0
	v_mad_u64_u32 v[2:3], s[0:1], s18, v2, v[130:131]
	v_add3_u32 v6, v6, v134, v132
	s_add_u32 s0, s60, s13
	v_mad_u64_u32 v[6:7], s[44:45], s18, v6, v[130:131]
	v_add_lshl_u32 v2, v2, v131, 1
	v_mov_b32_e32 v3, v1
	s_addc_u32 s1, s61, s5
	v_add_lshl_u32 v6, v6, v131, 1
	v_mov_b32_e32 v7, v1
	v_lshl_add_u64 v[148:149], s[0:1], 0, v[2:3]
	v_lshl_add_u64 v[150:151], s[0:1], 0, v[6:7]
	s_add_u32 s0, s60, s53
	s_addc_u32 s1, s61, s4
	v_lshl_add_u64 v[152:153], s[0:1], 0, v[2:3]
	v_mov_b32_e32 v2, 0
	v_lshl_add_u64 v[154:155], s[0:1], 0, v[6:7]
	v_lshl_add_u64 v[156:157], s[8:9], 0, v[4:5]
	s_mov_b32 s13, 0
	s_mov_b64 s[82:83], 0
	v_mov_b32_e32 v3, v2
	v_mov_b32_e32 v4, v2
	v_mov_b32_e32 v5, v2
	v_mov_b32_e32 v6, v2
	v_mov_b32_e32 v7, v2
	v_mov_b32_e32 v8, v2
	v_mov_b32_e32 v9, v2
	v_mov_b32_e32 v10, v2
	v_mov_b32_e32 v11, v2
	v_mov_b32_e32 v12, v2
	v_mov_b32_e32 v13, v2
	v_mov_b32_e32 v14, v2
	v_mov_b32_e32 v15, v2
	v_mov_b32_e32 v16, v2
	v_mov_b32_e32 v17, v2
	v_mov_b32_e32 v18, v2
	v_mov_b32_e32 v19, v2
	v_mov_b32_e32 v20, v2
	v_mov_b32_e32 v21, v2
	v_mov_b32_e32 v22, v2
	v_mov_b32_e32 v23, v2
	v_mov_b32_e32 v24, v2
	v_mov_b32_e32 v25, v2
	v_mov_b32_e32 v26, v2
	v_mov_b32_e32 v27, v2
	v_mov_b32_e32 v28, v2
	v_mov_b32_e32 v29, v2
	v_mov_b32_e32 v30, v2
	v_mov_b32_e32 v31, v2
	v_mov_b32_e32 v32, v2
	v_mov_b32_e32 v33, v2
	v_mov_b32_e32 v34, v2
	v_mov_b32_e32 v35, v2
	v_mov_b32_e32 v36, v2
	v_mov_b32_e32 v37, v2
	v_mov_b32_e32 v38, v2
	v_mov_b32_e32 v39, v2
	v_mov_b32_e32 v40, v2
	v_mov_b32_e32 v41, v2
	v_mov_b32_e32 v42, v2
	v_mov_b32_e32 v43, v2
	v_mov_b32_e32 v44, v2
	v_mov_b32_e32 v45, v2
	v_mov_b32_e32 v46, v2
	v_mov_b32_e32 v47, v2
	v_mov_b32_e32 v48, v2
	v_mov_b32_e32 v49, v2
	v_mov_b32_e32 v50, v2
	v_mov_b32_e32 v51, v2
	v_mov_b32_e32 v52, v2
	v_mov_b32_e32 v53, v2
	v_mov_b32_e32 v54, v2
	v_mov_b32_e32 v55, v2
	v_mov_b32_e32 v56, v2
	v_mov_b32_e32 v57, v2
	v_mov_b32_e32 v58, v2
	v_mov_b32_e32 v59, v2
	v_mov_b32_e32 v60, v2
	v_mov_b32_e32 v61, v2
	v_mov_b32_e32 v62, v2
	v_mov_b32_e32 v63, v2
	v_mov_b32_e32 v64, v2
	v_mov_b32_e32 v65, v2
	v_mov_b32_e32 v66, v2
	v_mov_b32_e32 v67, v2
	v_mov_b32_e32 v68, v2
	v_mov_b32_e32 v69, v2
	v_mov_b32_e32 v70, v2
	v_mov_b32_e32 v71, v2
	v_mov_b32_e32 v72, v2
	v_mov_b32_e32 v73, v2
	v_mov_b32_e32 v74, v2
	v_mov_b32_e32 v75, v2
	v_mov_b32_e32 v76, v2
	v_mov_b32_e32 v77, v2
	v_mov_b32_e32 v78, v2
	v_mov_b32_e32 v79, v2
	v_mov_b32_e32 v80, v2
	v_mov_b32_e32 v81, v2
	v_mov_b32_e32 v82, v2
	v_mov_b32_e32 v83, v2
	v_mov_b32_e32 v84, v2
	v_mov_b32_e32 v85, v2
	v_mov_b32_e32 v86, v2
	v_mov_b32_e32 v87, v2
	v_mov_b32_e32 v88, v2
	v_mov_b32_e32 v89, v2
	v_mov_b32_e32 v90, v2
	v_mov_b32_e32 v91, v2
	v_mov_b32_e32 v92, v2
	v_mov_b32_e32 v93, v2
	v_mov_b32_e32 v94, v2
	v_mov_b32_e32 v95, v2
	v_mov_b32_e32 v96, v2
	v_mov_b32_e32 v97, v2
	v_mov_b32_e32 v98, v2
	v_mov_b32_e32 v99, v2
	v_mov_b32_e32 v100, v2
	v_mov_b32_e32 v101, v2
	v_mov_b32_e32 v102, v2
	v_mov_b32_e32 v103, v2
	v_mov_b32_e32 v104, v2
	v_mov_b32_e32 v105, v2
	v_mov_b32_e32 v106, v2
	v_mov_b32_e32 v107, v2
	v_mov_b32_e32 v108, v2
	v_mov_b32_e32 v109, v2
	v_mov_b32_e32 v110, v2
	v_mov_b32_e32 v111, v2
	v_mov_b32_e32 v112, v2
	v_mov_b32_e32 v113, v2
	v_mov_b32_e32 v114, v2
	v_mov_b32_e32 v115, v2
	v_mov_b32_e32 v116, v2
	v_mov_b32_e32 v117, v2
	v_mov_b32_e32 v118, v2
	v_mov_b32_e32 v119, v2
	v_mov_b32_e32 v120, v2
	v_mov_b32_e32 v121, v2
	v_mov_b32_e32 v126, v2
	v_mov_b32_e32 v127, v2
	v_mov_b32_e32 v128, v2
	v_mov_b32_e32 v129, v2
	v_mov_b32_e32 v122, v2
	v_mov_b32_e32 v123, v2
	v_mov_b32_e32 v124, v2
	v_mov_b32_e32 v125, v2
	s_branch .LBB0_415
